# grid barrier: release counter polled with four loads in flight (destination registers v252-255 reserved for it) instead of one load per round trip
# baseline (speedup 1.0000x reference)
; __device__ __forceinline__ unsigned xb_ld(unsigned* p)              { return __hip_atomic_load(p, __ATOMIC_RELAXED, __HIP_MEMORY_SCOPE_AGENT); }
; __device__ __forceinline__ unsigned xb_add(unsigned* p, unsigned v) { return __hip_atomic_fetch_add(p, v, __ATOMIC_RELAXED, __HIP_MEMORY_SCOPE_AGENT); }
; #define XB_SPIN(cond, bar) do { unsigned _sp = 0; while (cond) { __builtin_amdgcn_s_sleep(1); \
;     if ((++_sp & 255u) == 0u) { if (xb_ld(&(bar)[XB_TMO])) break; if (_sp > XB_SPIN_CAP) { atomicAdd(&(bar)[XB_TMO], 1u); break; } } } } while (0)
; __device__ __forceinline__ void xcd_barrier(const XcdBarrier& b) {
;     ...
;             else XB_SPIN(xb_ld(&bar[XB_TOPGEN]) == tg, bar);
;             __builtin_amdgcn_fence(__ATOMIC_ACQUIRE, "agent");
;             xb_add(&bar[XB_XGEN(b.x)], 1u);
;             asm volatile("s_waitcnt vmcnt(0)" ::: "memory");
;         } else {
;             XB_SPIN(xb_ld(&bar[XB_XGEN(b.x)]) == gen, bar);
.Lmy_bar_poll_0:
	v_mov_b32_e32 v3, 0x3000
	s_mov_b32 s97, 0
	global_load_dword v252, v3, s[54:55] offset:1024 sc1
	s_sleep 3
	global_load_dword v253, v3, s[54:55] offset:1024 sc1
	s_sleep 3
	global_load_dword v254, v3, s[54:55] offset:1024 sc1
	s_sleep 3
.Lmy_bar_spin_0:
	global_load_dword v255, v3, s[54:55] offset:1024 sc1
	s_waitcnt vmcnt(3)
	v_readfirstlane_b32 s96, v252
	s_sub_i32 s96, s96, s99
	s_cmp_ge_i32 s96, 0
	s_cbranch_scc1 .Lmy_bar_go_0
	global_load_dword v252, v3, s[54:55] offset:1024 sc1
	s_waitcnt vmcnt(3)
	v_readfirstlane_b32 s96, v253
	s_sub_i32 s96, s96, s99
	s_cmp_ge_i32 s96, 0
	s_cbranch_scc1 .Lmy_bar_go_0
	global_load_dword v253, v3, s[54:55] offset:1024 sc1
	s_waitcnt vmcnt(3)
	v_readfirstlane_b32 s96, v254
	s_sub_i32 s96, s96, s99
	s_cmp_ge_i32 s96, 0
	s_cbranch_scc1 .Lmy_bar_go_0
	global_load_dword v254, v3, s[54:55] offset:1024 sc1
	s_waitcnt vmcnt(3)
	v_readfirstlane_b32 s96, v255
	s_sub_i32 s96, s96, s99
	s_cmp_ge_i32 s96, 0
	s_cbranch_scc1 .Lmy_bar_go_0
	s_add_i32 s97, s97, 1
	s_cmp_lt_u32 s97, 0x40000
	s_cbranch_scc1 .Lmy_bar_spin_0

; #define LAS __attribute__((address_space(3)))
; __global__ void __launch_bounds__(NT, 2) trunk_fwd(Args args) {
;     extern __shared__ __attribute__((aligned(16))) unsigned char lds_raw[];
;     LAS unsigned char* lds = (LAS unsigned char*)lds_raw;
;     cg::grid_group grid = cg::this_grid();
;     const Ptrs& P = args.p;
;     const int tid = threadIdx.x, lane = tid & 63, wave = __builtin_amdgcn_readfirstlane(tid >> 6);
	.amdhsa_kernel _Z9trunk_fwd4Args
		.amdhsa_group_segment_fixed_size 0
		.amdhsa_private_segment_fixed_size 0
		.amdhsa_kernarg_size 384
		.amdhsa_user_sgpr_count 2
		.amdhsa_user_sgpr_dispatch_ptr 0
		.amdhsa_user_sgpr_queue_ptr 0
		.amdhsa_user_sgpr_kernarg_segment_ptr 1
		.amdhsa_user_sgpr_dispatch_id 0
		.amdhsa_user_sgpr_kernarg_preload_length 0
		.amdhsa_user_sgpr_kernarg_preload_offset 0
		.amdhsa_user_sgpr_private_segment_size 0
		.amdhsa_uses_dynamic_stack 0
		.amdhsa_enable_private_segment 0
		.amdhsa_system_sgpr_workgroup_id_x 1
		.amdhsa_system_sgpr_workgroup_id_y 0
		.amdhsa_system_sgpr_workgroup_id_z 0
		.amdhsa_system_sgpr_workgroup_info 0
		.amdhsa_system_vgpr_workitem_id 2
		.amdhsa_next_free_vgpr 256
		.amdhsa_next_free_sgpr 101
		.amdhsa_accum_offset 256
		.amdhsa_reserve_vcc 1
		.amdhsa_float_round_mode_32 0
		.amdhsa_float_round_mode_16_64 0
		.amdhsa_float_denorm_mode_32 3
		.amdhsa_float_denorm_mode_16_64 3
		.amdhsa_dx10_clamp 1
		.amdhsa_ieee_mode 1
		.amdhsa_fp16_overflow 0
		.amdhsa_tg_split 0
		.amdhsa_exception_fp_ieee_invalid_op 0
		.amdhsa_exception_fp_denorm_src 0
		.amdhsa_exception_fp_ieee_div_zero 0
		.amdhsa_exception_fp_ieee_overflow 0
		.amdhsa_exception_fp_ieee_underflow 0
		.amdhsa_exception_fp_ieee_inexact 0
		.amdhsa_exception_int_div_zero 0
	.end_amdhsa_kernel

; __global__ void __launch_bounds__(NT, 2) trunk_fwd(Args args) {
amdhsa.kernels:
  - .agpr_count:     0
    .args:
      - .offset:         0
        .size:           128
        .value_kind:     by_value
      - .offset:         128
        .size:           4
        .value_kind:     hidden_block_count_x
      - .offset:         132
        .size:           4
        .value_kind:     hidden_block_count_y
      - .offset:         136
        .size:           4
        .value_kind:     hidden_block_count_z
      - .offset:         140
        .size:           2
        .value_kind:     hidden_group_size_x
      - .offset:         142
        .size:           2
        .value_kind:     hidden_group_size_y
      - .offset:         144
        .size:           2
        .value_kind:     hidden_group_size_z
      - .offset:         146
        .size:           2
        .value_kind:     hidden_remainder_x
      - .offset:         148
        .size:           2
        .value_kind:     hidden_remainder_y
      - .offset:         150
        .size:           2
        .value_kind:     hidden_remainder_z
      - .offset:         168
        .size:           8
        .value_kind:     hidden_global_offset_x
      - .offset:         176
        .size:           8
        .value_kind:     hidden_global_offset_y
      - .offset:         184
        .size:           8
        .value_kind:     hidden_global_offset_z
      - .offset:         192
        .size:           2
        .value_kind:     hidden_grid_dims
      - .offset:         216
        .size:           8
        .value_kind:     hidden_multigrid_sync_arg
      - .offset:         248
        .size:           4
        .value_kind:     hidden_dynamic_lds_size
    .group_segment_fixed_size: 0
    .kernarg_segment_align: 8
    .kernarg_segment_size: 384
    .language:       OpenCL C
    .language_version:
      - 2
      - 0
    .max_flat_workgroup_size: 512
    .name:           _Z9trunk_fwd4Args
    .private_segment_fixed_size: 0
    .sgpr_count:     107
    .sgpr_spill_count: 0
    .symbol:         _Z9trunk_fwd4Args.kd
    .uniform_work_group_size: 1
    .uses_dynamic_stack: false
    .vgpr_count:     256
    .vgpr_spill_count: 0
    .wavefront_size: 64
